# attention softmax max-trees: removed fmax-canonicalisation moves (v_max x,x) in MLA/SWA; 177 fewer VALU per key tile pair
# speedup vs baseline: 1.0071x; 1.0071x over previous
.LBB0_360:
	s_nop 10
	v_max_f32_e32 v0, v81, v97
	v_max_f32_e32 v4, v82, v98
	v_max3_f32 v0, v80, v96, v0
	v_max_f32_e32 v5, v83, v99
	v_max3_f32 v0, v0, v4, v5
	v_max_f32_e32 v4, v84, v100
	v_max_f32_e32 v5, v85, v101
	v_max3_f32 v0, v0, v4, v5
	v_max_f32_e32 v4, v86, v102
	v_max_f32_e32 v5, v87, v103
	v_max3_f32 v0, v0, v4, v5
	v_max_f32_e32 v4, v88, v104
	v_max_f32_e32 v5, v89, v105
	v_max3_f32 v0, v0, v4, v5
	v_max_f32_e32 v4, v90, v106
	v_max_f32_e32 v5, v91, v107
	v_max3_f32 v0, v0, v4, v5
	v_max_f32_e32 v4, v92, v108
	v_max_f32_e32 v5, v93, v109
	v_max3_f32 v0, v0, v4, v5
	v_max_f32_e32 v4, v94, v110
	v_max_f32_e32 v5, v95, v111
	s_cmp_eq_u32 s57, 0
	s_cselect_b64 s[10:11], -1, 0
	s_cmp_lg_u32 s57, 0
	v_max3_f32 v0, v0, v4, v5
	s_cbranch_scc0 .LBB0_368
	v_cmp_lt_f32_e32 vcc, s85, v0
	s_cmp_lg_u64 vcc, 0
	s_cselect_b64 s[36:37], -1, 0
	s_cbranch_execz .LBB0_369
	s_branch .LBB0_370

.LBB0_365:
	s_nop 10
	v_max_f32_e32 v0, v81, v97
	v_max_f32_e32 v3, v82, v98
	v_max3_f32 v0, v80, v96, v0
	v_max_f32_e32 v4, v83, v99
	v_max3_f32 v0, v0, v3, v4
	v_max_f32_e32 v3, v84, v100
	v_max_f32_e32 v4, v85, v101
	v_max3_f32 v0, v0, v3, v4
	v_max_f32_e32 v3, v86, v102
	v_max_f32_e32 v4, v87, v103
	v_max3_f32 v0, v0, v3, v4
	v_max_f32_e32 v3, v88, v104
	v_max_f32_e32 v4, v89, v105
	v_max3_f32 v0, v0, v3, v4
	v_max_f32_e32 v3, v90, v106
	v_max_f32_e32 v4, v91, v107
	v_max3_f32 v0, v0, v3, v4
	v_max_f32_e32 v3, v92, v108
	v_max_f32_e32 v4, v93, v109
	v_max3_f32 v0, v0, v3, v4
	v_max_f32_e32 v3, v94, v110
	v_max_f32_e32 v5, v95, v95
	v_max_f32_e32 v4, v5, v111
	v_max3_f32 v0, v0, v3, v4
	v_cmp_lt_f32_e32 vcc, s85, v0
	s_cbranch_vccz .LBB0_367
	ds_bpermute_b32 v3, v178, v0
	s_waitcnt lgkmcnt(0)
	v_max3_f32 v0, v0, v3, 0
	v_exp_f32_e64 v4, -v0
	v_add_f32_e32 v165, v165, v0
	v_xor_b32_e32 v64, 0x80000000, v165
	v_pk_add_f32 v[80:81], v[80:81], v[0:1] op_sel_hi:[1,0] neg_lo:[0,1] neg_hi:[0,1]
	v_pk_add_f32 v[96:97], v[96:97], v[0:1] op_sel_hi:[1,0] neg_lo:[0,1] neg_hi:[0,1]
	v_pk_add_f32 v[82:83], v[82:83], v[0:1] op_sel_hi:[1,0] neg_lo:[0,1] neg_hi:[0,1]
	v_pk_add_f32 v[98:99], v[98:99], v[0:1] op_sel_hi:[1,0] neg_lo:[0,1] neg_hi:[0,1]
	v_pk_add_f32 v[84:85], v[84:85], v[0:1] op_sel_hi:[1,0] neg_lo:[0,1] neg_hi:[0,1]
	v_pk_add_f32 v[100:101], v[100:101], v[0:1] op_sel_hi:[1,0] neg_lo:[0,1] neg_hi:[0,1]
	v_pk_add_f32 v[86:87], v[86:87], v[0:1] op_sel_hi:[1,0] neg_lo:[0,1] neg_hi:[0,1]
	v_pk_add_f32 v[102:103], v[102:103], v[0:1] op_sel_hi:[1,0] neg_lo:[0,1] neg_hi:[0,1]
	v_pk_add_f32 v[88:89], v[88:89], v[0:1] op_sel_hi:[1,0] neg_lo:[0,1] neg_hi:[0,1]
	v_pk_add_f32 v[104:105], v[104:105], v[0:1] op_sel_hi:[1,0] neg_lo:[0,1] neg_hi:[0,1]
	v_pk_add_f32 v[90:91], v[90:91], v[0:1] op_sel_hi:[1,0] neg_lo:[0,1] neg_hi:[0,1]
	v_pk_add_f32 v[106:107], v[106:107], v[0:1] op_sel_hi:[1,0] neg_lo:[0,1] neg_hi:[0,1]
	v_pk_add_f32 v[92:93], v[92:93], v[0:1] op_sel_hi:[1,0] neg_lo:[0,1] neg_hi:[0,1]
	v_pk_add_f32 v[108:109], v[108:109], v[0:1] op_sel_hi:[1,0] neg_lo:[0,1] neg_hi:[0,1]
	v_pk_add_f32 v[94:95], v[94:95], v[0:1] op_sel_hi:[1,0] neg_lo:[0,1] neg_hi:[0,1]
	v_pk_add_f32 v[110:111], v[110:111], v[0:1] op_sel_hi:[1,0] neg_lo:[0,1] neg_hi:[0,1]
	v_pk_mul_f32 v[62:63], v[62:63], v[4:5] op_sel_hi:[1,0]
	v_pk_mul_f32 v[60:61], v[60:61], v[4:5] op_sel_hi:[1,0]
	v_pk_mul_f32 v[58:59], v[58:59], v[4:5] op_sel_hi:[1,0]
	v_pk_mul_f32 v[56:57], v[56:57], v[4:5] op_sel_hi:[1,0]
	v_pk_mul_f32 v[54:55], v[54:55], v[4:5] op_sel_hi:[1,0]
	v_pk_mul_f32 v[52:53], v[52:53], v[4:5] op_sel_hi:[1,0]
	v_pk_mul_f32 v[50:51], v[50:51], v[4:5] op_sel_hi:[1,0]
	v_pk_mul_f32 v[48:49], v[48:49], v[4:5] op_sel_hi:[1,0]
	v_pk_mul_f32 v[46:47], v[46:47], v[4:5] op_sel_hi:[1,0]
	v_pk_mul_f32 v[44:45], v[44:45], v[4:5] op_sel_hi:[1,0]
	v_pk_mul_f32 v[42:43], v[42:43], v[4:5] op_sel_hi:[1,0]
	v_pk_mul_f32 v[40:41], v[40:41], v[4:5] op_sel_hi:[1,0]
	v_pk_mul_f32 v[38:39], v[38:39], v[4:5] op_sel_hi:[1,0]
	v_pk_mul_f32 v[36:37], v[36:37], v[4:5] op_sel_hi:[1,0]
	v_pk_mul_f32 v[34:35], v[34:35], v[4:5] op_sel_hi:[1,0]
	v_pk_mul_f32 v[32:33], v[32:33], v[4:5] op_sel_hi:[1,0]
	v_mov_b32_e32 v65, v64
	v_mov_b32_e32 v66, v64
	v_mov_b32_e32 v67, v64
	v_mov_b32_e32 v68, v64
	v_mov_b32_e32 v69, v64
	v_mov_b32_e32 v70, v64
	v_mov_b32_e32 v71, v64
	v_mov_b32_e32 v72, v64
	v_mov_b32_e32 v73, v64
	v_mov_b32_e32 v74, v64
	v_mov_b32_e32 v75, v64
	v_mov_b32_e32 v76, v64
	v_mov_b32_e32 v77, v64
	v_mov_b32_e32 v78, v64
	v_mov_b32_e32 v79, v64
	v_mul_f32_e32 v6, v6, v4

.LBB0_398:
	s_nop 10
	v_max_f32_e32 v0, v81, v97
	v_max_f32_e32 v4, v82, v98
	v_max3_f32 v0, v80, v96, v0
	v_max_f32_e32 v5, v83, v99
	v_max3_f32 v0, v0, v4, v5
	v_max_f32_e32 v4, v84, v100
	v_max_f32_e32 v5, v85, v101
	v_max3_f32 v0, v0, v4, v5
	v_max_f32_e32 v4, v86, v102
	v_max_f32_e32 v5, v87, v103
	v_max3_f32 v0, v0, v4, v5
	v_max_f32_e32 v4, v88, v104
	v_max_f32_e32 v5, v89, v105
	v_max3_f32 v0, v0, v4, v5
	v_max_f32_e32 v4, v90, v106
	v_max_f32_e32 v5, v91, v107
	v_max3_f32 v0, v0, v4, v5
	v_max_f32_e32 v4, v92, v108
	v_max_f32_e32 v5, v93, v109
	v_max3_f32 v0, v0, v4, v5
	v_max_f32_e32 v4, v94, v110
	v_max_f32_e32 v5, v95, v111
	s_cmp_eq_u32 s37, 0
	s_cselect_b64 s[10:11], -1, 0
	s_cmp_lg_u32 s37, 0
	v_max3_f32 v0, v0, v4, v5
	s_cbranch_scc0 .LBB0_406
	v_cmp_lt_f32_e32 vcc, s85, v0
	s_cmp_lg_u64 vcc, 0
	s_cselect_b64 s[16:17], -1, 0
	s_cbranch_execz .LBB0_407
	s_branch .LBB0_408

.LBB0_638:
	s_nop 10
	v_max_f32_e32 v0, v83, v67
	v_max_f32_e32 v3, v84, v68
	v_max3_f32 v0, v82, v66, v0
	v_max_f32_e32 v4, v85, v69
	v_max3_f32 v0, v0, v3, v4
	v_max_f32_e32 v3, v86, v70
	v_max_f32_e32 v4, v87, v71
	v_max3_f32 v0, v0, v3, v4
	v_max_f32_e32 v3, v88, v72
	v_max_f32_e32 v4, v89, v73
	v_max3_f32 v0, v0, v3, v4
	v_max_f32_e32 v3, v90, v74
	v_max_f32_e32 v4, v91, v75
	v_max3_f32 v0, v0, v3, v4
	v_max_f32_e32 v3, v92, v76
	v_max_f32_e32 v4, v93, v77
	v_max3_f32 v0, v0, v3, v4
	v_max_f32_e32 v3, v94, v78
	v_max_f32_e32 v4, v95, v79
	v_max3_f32 v0, v0, v3, v4
	v_max_f32_e32 v3, v96, v80
	v_max_f32_e32 v5, v97, v97
	v_max_f32_e32 v4, v5, v81
	v_max3_f32 v0, v0, v3, v4
	v_cmp_lt_f32_e32 vcc, s85, v0
	s_cbranch_vccz .LBB0_640
	ds_bpermute_b32 v3, v143, v0
	s_waitcnt lgkmcnt(0)
	v_max3_f32 v0, v0, v3, 0
	v_exp_f32_e64 v4, -v0
	v_add_f32_e32 v145, v145, v0
	v_xor_b32_e32 v50, 0x80000000, v145
	v_pk_add_f32 v[82:83], v[82:83], v[0:1] op_sel_hi:[1,0] neg_lo:[0,1] neg_hi:[0,1]
	v_pk_add_f32 v[66:67], v[66:67], v[0:1] op_sel_hi:[1,0] neg_lo:[0,1] neg_hi:[0,1]
	v_pk_add_f32 v[84:85], v[84:85], v[0:1] op_sel_hi:[1,0] neg_lo:[0,1] neg_hi:[0,1]
	v_pk_add_f32 v[68:69], v[68:69], v[0:1] op_sel_hi:[1,0] neg_lo:[0,1] neg_hi:[0,1]
	v_pk_add_f32 v[86:87], v[86:87], v[0:1] op_sel_hi:[1,0] neg_lo:[0,1] neg_hi:[0,1]
	v_pk_add_f32 v[70:71], v[70:71], v[0:1] op_sel_hi:[1,0] neg_lo:[0,1] neg_hi:[0,1]
	v_pk_add_f32 v[88:89], v[88:89], v[0:1] op_sel_hi:[1,0] neg_lo:[0,1] neg_hi:[0,1]
	v_pk_add_f32 v[72:73], v[72:73], v[0:1] op_sel_hi:[1,0] neg_lo:[0,1] neg_hi:[0,1]
	v_pk_add_f32 v[90:91], v[90:91], v[0:1] op_sel_hi:[1,0] neg_lo:[0,1] neg_hi:[0,1]
	v_pk_add_f32 v[74:75], v[74:75], v[0:1] op_sel_hi:[1,0] neg_lo:[0,1] neg_hi:[0,1]
	v_pk_add_f32 v[92:93], v[92:93], v[0:1] op_sel_hi:[1,0] neg_lo:[0,1] neg_hi:[0,1]
	v_pk_add_f32 v[76:77], v[76:77], v[0:1] op_sel_hi:[1,0] neg_lo:[0,1] neg_hi:[0,1]
	v_pk_add_f32 v[94:95], v[94:95], v[0:1] op_sel_hi:[1,0] neg_lo:[0,1] neg_hi:[0,1]
	v_pk_add_f32 v[78:79], v[78:79], v[0:1] op_sel_hi:[1,0] neg_lo:[0,1] neg_hi:[0,1]
	v_pk_add_f32 v[96:97], v[96:97], v[0:1] op_sel_hi:[1,0] neg_lo:[0,1] neg_hi:[0,1]
	v_pk_add_f32 v[80:81], v[80:81], v[0:1] op_sel_hi:[1,0] neg_lo:[0,1] neg_hi:[0,1]
	v_pk_mul_f32 v[48:49], v[48:49], v[4:5] op_sel_hi:[1,0]
	v_pk_mul_f32 v[46:47], v[46:47], v[4:5] op_sel_hi:[1,0]
	v_pk_mul_f32 v[44:45], v[44:45], v[4:5] op_sel_hi:[1,0]
	v_pk_mul_f32 v[42:43], v[42:43], v[4:5] op_sel_hi:[1,0]
	v_pk_mul_f32 v[40:41], v[40:41], v[4:5] op_sel_hi:[1,0]
	v_pk_mul_f32 v[38:39], v[38:39], v[4:5] op_sel_hi:[1,0]
	v_pk_mul_f32 v[36:37], v[36:37], v[4:5] op_sel_hi:[1,0]
	v_pk_mul_f32 v[34:35], v[34:35], v[4:5] op_sel_hi:[1,0]
	v_pk_mul_f32 v[32:33], v[32:33], v[4:5] op_sel_hi:[1,0]
	v_pk_mul_f32 v[30:31], v[30:31], v[4:5] op_sel_hi:[1,0]
	v_pk_mul_f32 v[28:29], v[28:29], v[4:5] op_sel_hi:[1,0]
	v_pk_mul_f32 v[26:27], v[26:27], v[4:5] op_sel_hi:[1,0]
	v_pk_mul_f32 v[24:25], v[24:25], v[4:5] op_sel_hi:[1,0]
	v_pk_mul_f32 v[22:23], v[22:23], v[4:5] op_sel_hi:[1,0]
	v_pk_mul_f32 v[20:21], v[20:21], v[4:5] op_sel_hi:[1,0]
	v_pk_mul_f32 v[18:19], v[18:19], v[4:5] op_sel_hi:[1,0]
	v_mov_b32_e32 v51, v50
	v_mov_b32_e32 v52, v50
	v_mov_b32_e32 v53, v50
	v_mov_b32_e32 v54, v50
	v_mov_b32_e32 v55, v50
	v_mov_b32_e32 v56, v50
	v_mov_b32_e32 v57, v50
	v_mov_b32_e32 v58, v50
	v_mov_b32_e32 v59, v50
	v_mov_b32_e32 v60, v50
	v_mov_b32_e32 v61, v50
	v_mov_b32_e32 v62, v50
	v_mov_b32_e32 v63, v50
	v_mov_b32_e32 v64, v50
	v_mov_b32_e32 v65, v50
	v_mul_f32_e32 v148, v148, v4

.LBB0_644:
	s_nop 10
	v_max_f32_e32 v0, v83, v67
	v_max_f32_e32 v2, v84, v68
	v_max3_f32 v0, v82, v66, v0
	v_max_f32_e32 v3, v85, v69
	v_max3_f32 v0, v0, v2, v3
	v_max_f32_e32 v2, v86, v70
	v_max_f32_e32 v3, v87, v71
	v_max3_f32 v0, v0, v2, v3
	v_max_f32_e32 v2, v88, v72
	v_max_f32_e32 v3, v89, v73
	v_max3_f32 v0, v0, v2, v3
	v_max_f32_e32 v2, v90, v74
	v_max_f32_e32 v3, v91, v75
	v_max3_f32 v0, v0, v2, v3
	v_max_f32_e32 v2, v92, v76
	v_max_f32_e32 v3, v93, v77
	v_max3_f32 v0, v0, v2, v3
	v_max_f32_e32 v2, v94, v78
	v_max_f32_e32 v3, v95, v79
	v_max3_f32 v0, v0, v2, v3
	v_max_f32_e32 v2, v96, v80
	v_max_f32_e32 v3, v97, v81
	v_max3_f32 v0, v0, v2, v3
	v_cmp_lt_f32_e32 vcc, s85, v0
	s_cbranch_vccz .LBB0_646
	ds_bpermute_b32 v2, v143, v0
	s_waitcnt lgkmcnt(0)
	v_max3_f32 v0, v0, v2, 0
	v_exp_f32_e64 v2, -v0
	v_add_f32_e32 v145, v145, v0
	v_xor_b32_e32 v50, 0x80000000, v145
	v_pk_add_f32 v[82:83], v[82:83], v[0:1] op_sel_hi:[1,0] neg_lo:[0,1] neg_hi:[0,1]
	v_pk_add_f32 v[66:67], v[66:67], v[0:1] op_sel_hi:[1,0] neg_lo:[0,1] neg_hi:[0,1]
	v_pk_add_f32 v[84:85], v[84:85], v[0:1] op_sel_hi:[1,0] neg_lo:[0,1] neg_hi:[0,1]
	v_pk_add_f32 v[68:69], v[68:69], v[0:1] op_sel_hi:[1,0] neg_lo:[0,1] neg_hi:[0,1]
	v_pk_add_f32 v[86:87], v[86:87], v[0:1] op_sel_hi:[1,0] neg_lo:[0,1] neg_hi:[0,1]
	v_pk_add_f32 v[70:71], v[70:71], v[0:1] op_sel_hi:[1,0] neg_lo:[0,1] neg_hi:[0,1]
	v_pk_add_f32 v[88:89], v[88:89], v[0:1] op_sel_hi:[1,0] neg_lo:[0,1] neg_hi:[0,1]
	v_pk_add_f32 v[72:73], v[72:73], v[0:1] op_sel_hi:[1,0] neg_lo:[0,1] neg_hi:[0,1]
	v_pk_add_f32 v[90:91], v[90:91], v[0:1] op_sel_hi:[1,0] neg_lo:[0,1] neg_hi:[0,1]
	v_pk_add_f32 v[74:75], v[74:75], v[0:1] op_sel_hi:[1,0] neg_lo:[0,1] neg_hi:[0,1]
	v_pk_add_f32 v[92:93], v[92:93], v[0:1] op_sel_hi:[1,0] neg_lo:[0,1] neg_hi:[0,1]
	v_pk_add_f32 v[76:77], v[76:77], v[0:1] op_sel_hi:[1,0] neg_lo:[0,1] neg_hi:[0,1]
	v_pk_add_f32 v[94:95], v[94:95], v[0:1] op_sel_hi:[1,0] neg_lo:[0,1] neg_hi:[0,1]
	v_pk_add_f32 v[78:79], v[78:79], v[0:1] op_sel_hi:[1,0] neg_lo:[0,1] neg_hi:[0,1]
	v_pk_add_f32 v[96:97], v[96:97], v[0:1] op_sel_hi:[1,0] neg_lo:[0,1] neg_hi:[0,1]
	v_pk_add_f32 v[80:81], v[80:81], v[0:1] op_sel_hi:[1,0] neg_lo:[0,1] neg_hi:[0,1]
	v_pk_mul_f32 v[48:49], v[48:49], v[2:3] op_sel_hi:[1,0]
	v_pk_mul_f32 v[46:47], v[46:47], v[2:3] op_sel_hi:[1,0]
	v_pk_mul_f32 v[44:45], v[44:45], v[2:3] op_sel_hi:[1,0]
	v_pk_mul_f32 v[42:43], v[42:43], v[2:3] op_sel_hi:[1,0]
	v_pk_mul_f32 v[40:41], v[40:41], v[2:3] op_sel_hi:[1,0]
	v_pk_mul_f32 v[38:39], v[38:39], v[2:3] op_sel_hi:[1,0]
	v_pk_mul_f32 v[36:37], v[36:37], v[2:3] op_sel_hi:[1,0]
	v_pk_mul_f32 v[34:35], v[34:35], v[2:3] op_sel_hi:[1,0]
	v_pk_mul_f32 v[32:33], v[32:33], v[2:3] op_sel_hi:[1,0]
	v_pk_mul_f32 v[30:31], v[30:31], v[2:3] op_sel_hi:[1,0]
	v_pk_mul_f32 v[28:29], v[28:29], v[2:3] op_sel_hi:[1,0]
	v_pk_mul_f32 v[26:27], v[26:27], v[2:3] op_sel_hi:[1,0]
	v_pk_mul_f32 v[24:25], v[24:25], v[2:3] op_sel_hi:[1,0]
	v_pk_mul_f32 v[22:23], v[22:23], v[2:3] op_sel_hi:[1,0]
	v_pk_mul_f32 v[20:21], v[20:21], v[2:3] op_sel_hi:[1,0]
	v_pk_mul_f32 v[18:19], v[18:19], v[2:3] op_sel_hi:[1,0]
	v_mov_b32_e32 v51, v50
	v_mov_b32_e32 v52, v50
	v_mov_b32_e32 v53, v50
	v_mov_b32_e32 v54, v50
	v_mov_b32_e32 v55, v50
	v_mov_b32_e32 v56, v50
	v_mov_b32_e32 v57, v50
	v_mov_b32_e32 v58, v50
	v_mov_b32_e32 v59, v50
	v_mov_b32_e32 v60, v50
	v_mov_b32_e32 v61, v50
	v_mov_b32_e32 v62, v50
	v_mov_b32_e32 v63, v50
	v_mov_b32_e32 v64, v50
	v_mov_b32_e32 v65, v50
	v_mul_f32_e32 v148, v148, v2
